# v40: heavy conv_run loops keep two tiles' loads in flight (unroll x2, X/Y register sets, 3-deep destination queue)
# baseline (speedup 1.0000x reference)
.LBB0_163:
	s_or_b64 exec, exec, s[0:1]
	s_or_b32 s34, s33, 7
	s_add_u32 s12, s82, 0x6400000
	s_addc_u32 s13, s83, 0
	s_add_u32 s14, s82, 0x6200000
	v_and_b32_e32 v39, 31, v0
	v_lshrrev_b32_e32 v163, 5, v0
	v_and_b32_e32 v41, 0x80, v0
	s_addc_u32 s15, s83, 0
	v_lshl_add_u32 v40, v39, 10, 0
	v_cmp_eq_u32_e64 s[0:1], 0, v41
	v_bitop3_b32 v41, v163, v0, 31 bitop3:0x78
	s_add_u32 s18, s82, 0x4200000
	v_lshl_add_u32 v50, v41, 2, v40
	v_bitop3_b32 v41, v163, v39, 16 bitop3:0x36
	s_addc_u32 s19, s83, 0
	v_lshl_add_u32 v49, v41, 2, v40
	v_bitop3_b32 v41, v163, v39, 32 bitop3:0x36
	v_bitop3_b32 v39, v163, v39, 48 bitop3:0x36
	v_readlane_b32 s36, v254, 46
	s_add_u32 s20, s82, 0x2200000
	v_lshlrev_b32_e32 v162, 4, v0
	s_movk_i32 s3, 0xf0
	v_lshl_add_u32 v48, v41, 2, v40
	v_lshl_add_u32 v39, v39, 2, v40
	v_or_b32_e32 v40, 32, v1
	v_readlane_b32 s50, v254, 60
	v_readlane_b32 s51, v254, 61
	s_addc_u32 s21, s83, 0
	v_lshl_add_u32 v44, v40, 8, 0
	v_bitop3_b32 v45, v40, s3, v162 bitop3:0x48
	v_or_b32_e32 v40, 64, v1
	s_cmp_eq_u64 s[50:51], 0
	v_lshl_add_u32 v47, v40, 8, 0
	v_bitop3_b32 v51, v40, s3, v162 bitop3:0x48
	v_or_b32_e32 v40, 0x60, v1
	s_cselect_b64 s[22:23], -1, 0
	s_add_u32 s24, s82, 0x1a00000
	v_readlane_b32 s10, v254, 3
	v_lshlrev_b32_e32 v37, 3, v0
	v_bitop3_b32 v43, v1, s3, v162 bitop3:0x48
	v_bitop3_b32 v55, v40, s3, v162 bitop3:0x48
	s_addc_u32 s25, s83, 0
	s_lshl_b32 s3, s10, 10
	v_and_b32_e32 v38, 0x78, v37
	v_mov_b32_e32 v37, 0
	s_or_b32 s35, s3, 0x80
	s_lshl_b32 s3, s10, 6
	v_and_b32_e32 v164, 64, v0
	v_lshl_add_u32 v42, v1, 8, 0
	v_lshl_add_u32 v54, v40, 8, 0
	v_lshlrev_b32_e32 v40, 2, v46
	v_mov_b32_e32 v41, v37
	v_readlane_b32 s37, v254, 47
	v_readlane_b32 s38, v254, 48
	s_or_b32 s36, s3, 8
	s_lshl_b32 s3, s10, 4
	s_mov_b32 s11, 0
	v_cmp_eq_u32_e64 s[4:5], 0, v164
	v_lshl_add_u64 v[40:41], s[50:51], 0, v[40:41]
	s_or_b32 s37, s3, 2
	v_add_u32_e32 v53, v42, v43
	v_add_u32_e32 v52, v44, v45
	v_add_u32_e32 v51, v47, v51
	v_add_u32_e32 v47, v54, v55
	s_mov_b32 s38, 0
	v_readlane_b32 s39, v254, 49
	v_readlane_b32 s40, v254, 50
	v_readlane_b32 s41, v254, 51
	v_readlane_b32 s42, v254, 52
	v_readlane_b32 s43, v254, 53
	v_readlane_b32 s44, v254, 54
	v_readlane_b32 s45, v254, 55
	v_readlane_b32 s46, v254, 56
	v_readlane_b32 s47, v254, 57
	v_readlane_b32 s48, v254, 58
	v_readlane_b32 s49, v254, 59
	global_load_dword v238, v[34:35], off
	global_load_dword v238, v[34:35], off
	global_load_dword v238, v[34:35], off
	global_load_dword v238, v[34:35], off
	s_add_i32 s10, s33, s38
	s_cmpk_gt_i32 s10, 0xfe
	s_mov_b64 s[30:31], -1
	s_cbranch_scc0 .LBB0_178_s
	s_cmpk_gt_u32 s10, 0x4fe
	s_mov_b64 s[28:29], -1
	s_cbranch_scc0 .LBB0_176_s
	s_cmpk_gt_u32 s10, 0x8fe
	s_cbranch_scc0 .LBB0_173_s
	s_and_b32 s3, s35, 0x780
	s_cmpk_gt_u32 s10, 0x91e
	v_or_b32_e32 v116, s3, v1
	s_mov_b64 s[26:27], -1
	s_cbranch_scc0 .LBB0_170_s
	s_and_b32 s10, s36, 0xffffff80
	v_lshlrev_b32_e32 v114, 12, v116
	v_mov_b32_e32 v115, v37
	s_addk_i32 s10, 0xb700
	v_lshl_add_u64 v[114:115], s[12:13], 0, v[114:115]
	v_lshl_add_u64 v[114:115], s[10:11], 1, v[114:115]
	v_lshlrev_b32_e32 v118, 1, v38
	v_mov_b32_e32 v119, v37
	v_lshl_add_u64 v[42:43], v[114:115], 0, v[118:119]
	v_or_b32_e32 v114, s10, v46
	v_mov_b32_e32 v115, v37
	v_lshlrev_b64 v[114:115], 13, v[114:115]
	v_lshl_add_u64 v[114:115], s[76:77], 0, v[114:115]
	s_lshl_b32 s10, s3, 2
	v_lshl_add_u64 v[114:115], v[114:115], 0, s[10:11]
	s_mov_b64 s[26:27], 0
.LBB0_170_s:
	s_andn2_b64 vcc, exec, s[26:27]
	s_movk_i32 s26, 0x800
	s_cbranch_vccnz .LBB0_172_s
	s_and_b32 s10, s36, 0x7f80
	v_lshlrev_b32_e32 v114, 9, v116
	v_mov_b32_e32 v115, v37
	s_addk_i32 s10, 0xb800
	v_lshl_add_u64 v[114:115], s[14:15], 0, v[114:115]
	v_lshl_add_u64 v[114:115], s[10:11], 1, v[114:115]
	v_lshlrev_b32_e32 v116, 1, v38
	v_mov_b32_e32 v117, v37
	v_lshl_add_u64 v[42:43], v[114:115], 0, v[116:117]
	v_or_b32_e32 v114, s10, v46
	v_mov_b32_e32 v115, v37
	v_lshlrev_b64 v[114:115], 13, v[114:115]
	v_lshl_add_u64 v[114:115], s[72:73], 0, v[114:115]
	s_lshl_b32 s10, s3, 2
	v_lshl_add_u64 v[114:115], v[114:115], 0, s[10:11]
	s_movk_i32 s26, 0x100

.LBB0_173_s:
	s_andn2_b64 vcc, exec, s[28:29]
	s_cbranch_vccnz .LBB0_175_s
	s_and_b32 s3, s36, 0x7f80
	s_add_i32 s10, s3, 0xffffd800
	s_and_b32 s3, s35, 0x780
	v_or_b32_e32 v114, s3, v1
	v_lshlrev_b32_e32 v114, 14, v114
	v_mov_b32_e32 v115, v37
	v_lshl_add_u64 v[114:115], s[18:19], 0, v[114:115]
	v_lshl_add_u64 v[114:115], s[10:11], 1, v[114:115]
	v_lshlrev_b32_e32 v116, 1, v38
	v_mov_b32_e32 v117, v37
	v_lshl_add_u64 v[42:43], v[114:115], 0, v[116:117]
	v_or_b32_e32 v114, s10, v46
	v_mov_b32_e32 v115, v37
	v_lshlrev_b64 v[114:115], 13, v[114:115]
	v_lshl_add_u64 v[114:115], s[70:71], 0, v[114:115]
	s_lshl_b32 s10, s3, 2
	v_lshl_add_u64 v[114:115], v[114:115], 0, s[10:11]
	s_movk_i32 s26, 0x2000

.LBB0_176_s:
	s_andn2_b64 vcc, exec, s[28:29]
	s_cbranch_vccnz .LBB0_192_s
	s_and_b32 s3, s37, 0xf80
	s_add_i32 s10, s3, 0xfffffe00
	v_lshl_add_u64 v[114:115], s[10:11], 2, v[40:41]
	s_and_b32 s3, s35, 0x1f80
	v_cndmask_b32_e64 v44, v114, 0, s[22:23]
	v_or_b32_e32 v114, s3, v1
	v_cndmask_b32_e64 v45, v115, 0, s[22:23]
	v_lshlrev_b32_e32 v114, 12, v114
	v_mov_b32_e32 v115, v37
	v_lshl_add_u64 v[114:115], s[20:21], 0, v[114:115]
	v_lshl_add_u64 v[114:115], s[10:11], 1, v[114:115]
	v_lshlrev_b32_e32 v116, 1, v38
	v_mov_b32_e32 v117, v37
	v_lshl_add_u64 v[42:43], v[114:115], 0, v[116:117]
	v_or_b32_e32 v114, s10, v46
	v_mov_b32_e32 v115, v37
	v_lshlrev_b64 v[114:115], 15, v[114:115]
	v_lshl_add_u64 v[114:115], s[68:69], 0, v[114:115]
	s_lshl_b32 s10, s3, 2
	v_lshl_add_u64 v[114:115], v[114:115], 0, s[10:11]
	s_mov_b64 s[28:29], 0x2000
	s_movk_i32 s26, 0x800
	s_mov_b64 s[30:31], 0

.LBB0_179_s:
	s_and_b32 s3, s35, 0x780
	v_or_b32_e32 v114, s3, v1
	s_and_b32 s26, s36, 0xffffff80
	v_lshlrev_b32_e32 v114, 12, v114
	v_mov_b32_e32 v115, v37
	s_ashr_i32 s27, s26, 31
	v_lshl_add_u64 v[114:115], s[24:25], 0, v[114:115]
	v_lshl_add_u64 v[114:115], s[26:27], 1, v[114:115]
	v_lshlrev_b32_e32 v116, 1, v38
	v_mov_b32_e32 v117, v37
	v_lshl_add_u64 v[42:43], v[114:115], 0, v[116:117]
	v_or_b32_e32 v114, s26, v46
	v_ashrrev_i32_e32 v115, 31, v114
	v_readlane_b32 s40, v254, 46
	v_lshlrev_b64 v[114:115], 13, v[114:115]
	v_readlane_b32 s52, v254, 58
	v_readlane_b32 s53, v254, 59
	s_lshl_b32 s10, s3, 2
	s_movk_i32 s26, 0x800
	v_lshl_add_u64 v[114:115], s[52:53], 0, v[114:115]
	v_lshl_add_u64 v[114:115], v[114:115], 0, s[10:11]
	s_mov_b64 s[28:29], 0x800
	v_mov_b64_e32 v[44:45], 0
	v_readlane_b32 s41, v254, 47
	v_readlane_b32 s42, v254, 48
	v_readlane_b32 s43, v254, 49
	v_readlane_b32 s44, v254, 50
	v_readlane_b32 s45, v254, 51
	v_readlane_b32 s46, v254, 52
	v_readlane_b32 s47, v254, 53
	v_readlane_b32 s48, v254, 54
	v_readlane_b32 s49, v254, 55
	v_readlane_b32 s50, v254, 56
	v_readlane_b32 s51, v254, 57
	v_readlane_b32 s54, v254, 60
	v_readlane_b32 s55, v254, 61
.LBB0_180_s:
	v_lshl_add_u64 v[114:115], v[114:115], 0, v[36:37]
	v_lshl_add_u64 v[122:123], s[28:29], 2, v[114:115]
	global_load_dwordx4 v[114:117], v[114:115], off
	s_nop 0
	global_load_dwordx4 v[118:121], v[122:123], off
	v_mov_b32_e32 v146, 1.0
	v_mov_b32_e32 v147, 1.0
	v_mov_b32_e32 v148, 1.0
	v_mov_b32_e32 v149, 1.0
	v_mov_b32_e32 v150, 1.0
	v_mov_b32_e32 v151, 1.0
	v_mov_b32_e32 v152, 1.0
	v_mov_b32_e32 v153, 1.0
	v_cmp_ne_u64_e32 vcc, 0, v[44:45]
	s_and_saveexec_b64 s[30:31], vcc
	s_cbranch_execz .LBB0_182_s
	global_load_dwordx2 v[146:147], v[44:45], off
.LBB0_182_s:
	s_or_b64 exec, exec, s[30:31]
	s_mul_i32 s10, s28, 0x7c
	v_lshl_add_u64 v[122:123], v[122:123], 0, s[10:11]
	s_lshl_b64 s[28:29], s[28:29], 2
	v_lshl_add_u64 v[130:131], v[122:123], 0, s[28:29]
	global_load_dwordx4 v[122:125], v[122:123], off
	s_nop 0
	global_load_dwordx4 v[126:129], v[130:131], off
	s_and_saveexec_b64 s[30:31], vcc
	s_cbranch_execz .LBB0_184_s
	global_load_dwordx2 v[148:149], v[44:45], off offset:128
.LBB0_184_s:
	s_or_b64 exec, exec, s[30:31]
	v_lshl_add_u64 v[130:131], v[130:131], 0, s[10:11]
	v_lshl_add_u64 v[138:139], v[130:131], 0, s[28:29]
	global_load_dwordx4 v[130:133], v[130:131], off
	s_nop 0
	global_load_dwordx4 v[134:137], v[138:139], off
	s_and_saveexec_b64 s[30:31], vcc
	s_cbranch_execz .LBB0_186_s
	global_load_dwordx2 v[150:151], v[44:45], off offset:256
.LBB0_186_s:
	s_or_b64 exec, exec, s[30:31]
	v_lshl_add_u64 v[138:139], v[138:139], 0, s[10:11]
	v_lshl_add_u64 v[142:143], v[138:139], 0, s[28:29]
	global_load_dwordx4 v[138:141], v[138:139], off
	s_nop 0
	global_load_dwordx4 v[142:145], v[142:143], off
	s_and_saveexec_b64 s[28:29], vcc
	s_cbranch_execz .LBB0_188_s
	global_load_dwordx2 v[152:153], v[44:45], off offset:384

.Lc5_hb_sd:
	v_mov_b64_e32 v[236:237], v[42:43]
	s_mov_b32 s96, s26
	s_addk_i32 s35, 0x80
	s_add_i32 s36, s36, 8
	s_add_i32 s37, s37, 2
	global_load_dword v238, v[34:35], off
	global_load_dword v238, v[34:35], off
	global_load_dword v238, v[34:35], off
	global_load_dword v238, v[34:35], off
.LBB0_164:
	s_waitcnt vmcnt(16)
	v_mov_b64_e32 v[72:73], v[2:3]
	v_mov_b64_e32 v[74:75], v[4:5]
	v_mov_b64_e32 v[76:77], v[6:7]
	v_mov_b64_e32 v[78:79], v[8:9]
	v_mov_b64_e32 v[80:81], v[10:11]
	v_mov_b64_e32 v[82:83], v[12:13]
	v_mov_b64_e32 v[84:85], v[14:15]
	v_mov_b64_e32 v[86:87], v[16:17]
	v_mov_b64_e32 v[88:89], v[18:19]
	v_mov_b64_e32 v[90:91], v[20:21]
	v_mov_b64_e32 v[92:93], v[22:23]
	v_mov_b64_e32 v[94:95], v[24:25]
	v_mov_b64_e32 v[96:97], v[26:27]
	v_mov_b64_e32 v[98:99], v[28:29]
	v_mov_b64_e32 v[100:101], v[30:31]
	v_mov_b64_e32 v[102:103], v[32:33]
	v_mov_b64_e32 v[104:105], v[64:65]
	v_mov_b64_e32 v[106:107], v[66:67]
	v_mov_b64_e32 v[108:109], v[68:69]
	v_mov_b64_e32 v[110:111], v[70:71]
	s_add_i32 s10, s33, s38
	s_add_i32 s10, s10, 1
	s_cmp_ge_i32 s10, s34
	s_cbranch_scc1 .LBB0_189
	s_cmpk_gt_i32 s10, 0xfe
	s_mov_b64 s[30:31], -1
	s_cbranch_scc0 .LBB0_178
	s_cmpk_gt_u32 s10, 0x4fe
	s_mov_b64 s[28:29], -1
	s_cbranch_scc0 .LBB0_176
	s_cmpk_gt_u32 s10, 0x8fe
	s_cbranch_scc0 .LBB0_173
	s_and_b32 s3, s35, 0x780
	s_cmpk_gt_u32 s10, 0x91e
	v_or_b32_e32 v4, s3, v1
	s_mov_b64 s[26:27], -1
	s_cbranch_scc0 .LBB0_170
	s_and_b32 s10, s36, 0xffffff80
	v_lshlrev_b32_e32 v2, 12, v4
	v_mov_b32_e32 v3, v37
	s_addk_i32 s10, 0xb700
	v_lshl_add_u64 v[2:3], s[12:13], 0, v[2:3]
	v_lshl_add_u64 v[2:3], s[10:11], 1, v[2:3]
	v_lshlrev_b32_e32 v6, 1, v38
	v_mov_b32_e32 v7, v37
	v_lshl_add_u64 v[42:43], v[2:3], 0, v[6:7]
	v_or_b32_e32 v2, s10, v46
	v_mov_b32_e32 v3, v37
	v_lshlrev_b64 v[2:3], 13, v[2:3]
	v_lshl_add_u64 v[2:3], s[76:77], 0, v[2:3]
	s_lshl_b32 s10, s3, 2
	v_lshl_add_u64 v[2:3], v[2:3], 0, s[10:11]
	s_mov_b64 s[26:27], 0

.LBB0_189:
	s_mov_b32 s26, s2
	v_mov_b64_e32 v[42:43], v[34:35]
	s_waitcnt vmcnt(4)

.LBB0_190:
	ds_read_b128 v[54:57], v53
	s_mov_b32 s3, s11
	s_lshl_b64 s[2:3], s[2:3], 6
	s_add_i32 s38, s38, 1
	s_addk_i32 s35, 0x80
	s_waitcnt lgkmcnt(0)
	v_cndmask_b32_e64 v44, v55, v54, s[4:5]
	v_cndmask_b32_e64 v45, v54, v55, s[4:5]
	v_cndmask_b32_e64 v58, v57, v56, s[4:5]
	v_cndmask_b32_e64 v57, v56, v57, s[4:5]
	v_cndmask_b32_e64 v54, v58, v44, s[0:1]
	v_cndmask_b32_e64 v55, v57, v45, s[0:1]
	v_cndmask_b32_e64 v56, v44, v58, s[0:1]
	v_cndmask_b32_e64 v57, v45, v57, s[0:1]
	global_store_dwordx4 v[34:35], v[54:57], off
	ds_read_b128 v[54:57], v52
	v_lshl_add_u64 v[34:35], v[34:35], 0, s[2:3]
	s_add_i32 s36, s36, 8
	s_add_i32 s37, s37, 2
	s_cmp_lg_u32 s38, 7
	s_waitcnt lgkmcnt(0)
	v_cndmask_b32_e64 v44, v55, v54, s[4:5]
	v_cndmask_b32_e64 v45, v54, v55, s[4:5]
	v_cndmask_b32_e64 v58, v57, v56, s[4:5]
	v_cndmask_b32_e64 v57, v56, v57, s[4:5]
	v_cndmask_b32_e64 v54, v58, v44, s[0:1]
	v_cndmask_b32_e64 v55, v57, v45, s[0:1]
	v_cndmask_b32_e64 v56, v44, v58, s[0:1]
	v_cndmask_b32_e64 v57, v45, v57, s[0:1]
	global_store_dwordx4 v[34:35], v[54:57], off
	ds_read_b128 v[54:57], v51
	v_lshl_add_u64 v[34:35], v[34:35], 0, s[2:3]
	s_waitcnt lgkmcnt(0)
	v_cndmask_b32_e64 v44, v55, v54, s[4:5]
	v_cndmask_b32_e64 v45, v54, v55, s[4:5]
	v_cndmask_b32_e64 v58, v57, v56, s[4:5]
	v_cndmask_b32_e64 v57, v56, v57, s[4:5]
	v_cndmask_b32_e64 v54, v58, v44, s[0:1]
	v_cndmask_b32_e64 v55, v57, v45, s[0:1]
	v_cndmask_b32_e64 v56, v44, v58, s[0:1]
	v_cndmask_b32_e64 v57, v45, v57, s[0:1]
	global_store_dwordx4 v[34:35], v[54:57], off
	ds_read_b128 v[54:57], v47
	v_lshl_add_u64 v[34:35], v[34:35], 0, s[2:3]
	s_waitcnt lgkmcnt(0)
	v_cndmask_b32_e64 v44, v55, v54, s[4:5]
	v_cndmask_b32_e64 v45, v54, v55, s[4:5]
	v_cndmask_b32_e64 v58, v57, v56, s[4:5]
	v_cndmask_b32_e64 v57, v56, v57, s[4:5]
	v_cndmask_b32_e64 v54, v58, v44, s[0:1]
	v_cndmask_b32_e64 v55, v57, v45, s[0:1]
	v_cndmask_b32_e64 v56, v44, v58, s[0:1]
	v_cndmask_b32_e64 v57, v45, v57, s[0:1]
	global_store_dwordx4 v[34:35], v[54:57], off
	s_barrier
	s_mov_b32 s2, s96
	v_mov_b64_e32 v[34:35], v[236:237]
	s_mov_b32 s96, s26
	v_mov_b64_e32 v[236:237], v[42:43]
.Lc5_hb_b:
	s_waitcnt vmcnt(16)
	v_mov_b64_e32 v[72:73], v[114:115]
	v_mov_b64_e32 v[74:75], v[116:117]
	v_mov_b64_e32 v[76:77], v[118:119]
	v_mov_b64_e32 v[78:79], v[120:121]
	v_mov_b64_e32 v[80:81], v[122:123]
	v_mov_b64_e32 v[82:83], v[124:125]
	v_mov_b64_e32 v[84:85], v[126:127]
	v_mov_b64_e32 v[86:87], v[128:129]
	v_mov_b64_e32 v[88:89], v[130:131]
	v_mov_b64_e32 v[90:91], v[132:133]
	v_mov_b64_e32 v[92:93], v[134:135]
	v_mov_b64_e32 v[94:95], v[136:137]
	v_mov_b64_e32 v[96:97], v[138:139]
	v_mov_b64_e32 v[98:99], v[140:141]
	v_mov_b64_e32 v[100:101], v[142:143]
	v_mov_b64_e32 v[102:103], v[144:145]
	v_mov_b64_e32 v[104:105], v[146:147]
	v_mov_b64_e32 v[106:107], v[148:149]
	v_mov_b64_e32 v[108:109], v[150:151]
	v_mov_b64_e32 v[110:111], v[152:153]
	s_add_i32 s10, s33, s38
	s_add_i32 s10, s10, 1
	s_cmp_ge_i32 s10, s34
	s_cbranch_scc1 .LBB0_189_b
	s_cmpk_gt_i32 s10, 0xfe
	s_mov_b64 s[30:31], -1
	s_cbranch_scc0 .LBB0_178_b
	s_cmpk_gt_u32 s10, 0x4fe
	s_mov_b64 s[28:29], -1
	s_cbranch_scc0 .LBB0_176_b
	s_cmpk_gt_u32 s10, 0x8fe
	s_cbranch_scc0 .LBB0_173_b
	s_and_b32 s3, s35, 0x780
	s_cmpk_gt_u32 s10, 0x91e
	v_or_b32_e32 v116, s3, v1
	s_mov_b64 s[26:27], -1
	s_cbranch_scc0 .LBB0_170_b
	s_and_b32 s10, s36, 0xffffff80
	v_lshlrev_b32_e32 v114, 12, v116
	v_mov_b32_e32 v115, v37
	s_addk_i32 s10, 0xb700
	v_lshl_add_u64 v[114:115], s[12:13], 0, v[114:115]
	v_lshl_add_u64 v[114:115], s[10:11], 1, v[114:115]
	v_lshlrev_b32_e32 v118, 1, v38
	v_mov_b32_e32 v119, v37
	v_lshl_add_u64 v[42:43], v[114:115], 0, v[118:119]
	v_or_b32_e32 v114, s10, v46
	v_mov_b32_e32 v115, v37
	v_lshlrev_b64 v[114:115], 13, v[114:115]
	v_lshl_add_u64 v[114:115], s[76:77], 0, v[114:115]
	s_lshl_b32 s10, s3, 2
	v_lshl_add_u64 v[114:115], v[114:115], 0, s[10:11]
	s_mov_b64 s[26:27], 0

.LBB0_190_b:
	ds_read_b128 v[54:57], v53
	s_mov_b32 s3, s11
	s_lshl_b64 s[2:3], s[2:3], 6
	s_add_i32 s38, s38, 1
	s_addk_i32 s35, 0x80
	s_waitcnt lgkmcnt(0)
	v_cndmask_b32_e64 v44, v55, v54, s[4:5]
	v_cndmask_b32_e64 v45, v54, v55, s[4:5]
	v_cndmask_b32_e64 v58, v57, v56, s[4:5]
	v_cndmask_b32_e64 v57, v56, v57, s[4:5]
	v_cndmask_b32_e64 v54, v58, v44, s[0:1]
	v_cndmask_b32_e64 v55, v57, v45, s[0:1]
	v_cndmask_b32_e64 v56, v44, v58, s[0:1]
	v_cndmask_b32_e64 v57, v45, v57, s[0:1]
	global_store_dwordx4 v[34:35], v[54:57], off
	ds_read_b128 v[54:57], v52
	v_lshl_add_u64 v[34:35], v[34:35], 0, s[2:3]
	s_add_i32 s36, s36, 8
	s_add_i32 s37, s37, 2
	s_cmp_lg_u32 s38, 8
	s_waitcnt lgkmcnt(0)
	v_cndmask_b32_e64 v44, v55, v54, s[4:5]
	v_cndmask_b32_e64 v45, v54, v55, s[4:5]
	v_cndmask_b32_e64 v58, v57, v56, s[4:5]
	v_cndmask_b32_e64 v57, v56, v57, s[4:5]
	v_cndmask_b32_e64 v54, v58, v44, s[0:1]
	v_cndmask_b32_e64 v55, v57, v45, s[0:1]
	v_cndmask_b32_e64 v56, v44, v58, s[0:1]
	v_cndmask_b32_e64 v57, v45, v57, s[0:1]
	global_store_dwordx4 v[34:35], v[54:57], off
	ds_read_b128 v[54:57], v51
	v_lshl_add_u64 v[34:35], v[34:35], 0, s[2:3]
	s_waitcnt lgkmcnt(0)
	v_cndmask_b32_e64 v44, v55, v54, s[4:5]
	v_cndmask_b32_e64 v45, v54, v55, s[4:5]
	v_cndmask_b32_e64 v58, v57, v56, s[4:5]
	v_cndmask_b32_e64 v57, v56, v57, s[4:5]
	v_cndmask_b32_e64 v54, v58, v44, s[0:1]
	v_cndmask_b32_e64 v55, v57, v45, s[0:1]
	v_cndmask_b32_e64 v56, v44, v58, s[0:1]
	v_cndmask_b32_e64 v57, v45, v57, s[0:1]
	global_store_dwordx4 v[34:35], v[54:57], off
	ds_read_b128 v[54:57], v47
	v_lshl_add_u64 v[34:35], v[34:35], 0, s[2:3]
	s_waitcnt lgkmcnt(0)
	v_cndmask_b32_e64 v44, v55, v54, s[4:5]
	v_cndmask_b32_e64 v45, v54, v55, s[4:5]
	v_cndmask_b32_e64 v58, v57, v56, s[4:5]
	v_cndmask_b32_e64 v57, v56, v57, s[4:5]
	v_cndmask_b32_e64 v54, v58, v44, s[0:1]
	v_cndmask_b32_e64 v55, v57, v45, s[0:1]
	v_cndmask_b32_e64 v56, v44, v58, s[0:1]
	v_cndmask_b32_e64 v57, v45, v57, s[0:1]
	global_store_dwordx4 v[34:35], v[54:57], off
	s_barrier
	s_cbranch_scc0 .Lc5_hb_x
	s_mov_b32 s2, s96
	v_mov_b64_e32 v[34:35], v[236:237]
	s_mov_b32 s96, s26
	v_mov_b64_e32 v[236:237], v[42:43]
	s_branch .LBB0_164
.LBB0_192:
	v_mov_b64_e32 v[44:45], 0
	s_mov_b64 s[28:29], 0x800
	s_cbranch_execz .LBB0_179
	s_branch .LBB0_180
.LBB0_192_b:
	v_mov_b64_e32 v[44:45], 0
	s_mov_b64 s[28:29], 0x800
	s_cbranch_execz .LBB0_179_b
	s_branch .LBB0_180_b
.LBB0_192_s:
	v_mov_b64_e32 v[44:45], 0
	s_mov_b64 s[28:29], 0x800
	s_cbranch_execz .LBB0_179_s
	s_branch .LBB0_180_s
.Lc5_hb_x:
	s_branch .LBB0_195
.LBB0_194:
	v_lshrrev_b32_e32 v1, 4, v0
	v_lshlrev_b32_e32 v162, 4, v0
	v_and_b32_e32 v164, 64, v0
	v_lshrrev_b32_e32 v163, 5, v0
	v_lshlrev_b32_e32 v161, 2, v0

.LBB0_456:
	s_or_b64 exec, exec, s[0:1]
	s_or_b32 s29, s28, 7
	s_add_u32 s8, s82, 0x6400000
	s_addc_u32 s9, s83, 0
	s_add_u32 s10, s82, 0x6200000
	v_and_b32_e32 v39, 31, v0
	v_and_b32_e32 v41, 0x80, v0
	s_addc_u32 s11, s83, 0
	v_lshl_add_u32 v40, v39, 10, 0
	v_cmp_eq_u32_e64 s[0:1], 0, v41
	v_bitop3_b32 v41, v163, v0, 31 bitop3:0x78
	v_bitop3_b32 v39, v163, v39, 32 bitop3:0x36
	s_add_u32 s12, s82, 0x4200000
	v_lshl_add_u32 v50, v41, 2, v40
	v_add_u32_e32 v41, 16, v163
	v_lshl_add_u32 v47, v39, 2, v40
	v_add_u32_e32 v39, 48, v163
	s_addc_u32 s13, s83, 0
	v_bitop3_b32 v41, v41, v0, 31 bitop3:0x78
	v_bitop3_b32 v39, v39, v0, 31 bitop3:0x78
	v_readlane_b32 s48, v254, 46
	s_add_u32 s14, s82, 0x2200000
	s_movk_i32 s3, 0xf0
	v_lshl_add_u32 v49, v41, 2, v40
	v_lshl_add_u32 v39, v39, 2, v40
	v_add_u32_e32 v40, 32, v1
	v_readlane_b32 s62, v254, 60
	v_readlane_b32 s63, v254, 61
	s_addc_u32 s15, s83, 0
	v_lshl_add_u32 v44, v40, 8, 0
	v_bitop3_b32 v45, v40, s3, v162 bitop3:0x48
	v_or_b32_e32 v40, 64, v1
	s_cmp_eq_u64 s[62:63], 0
	v_lshl_add_u32 v46, v40, 8, 0
	v_bitop3_b32 v51, v40, s3, v162 bitop3:0x48
	v_add_u32_e32 v40, 0x60, v1
	s_cselect_b64 s[18:19], -1, 0
	s_add_u32 s20, s82, 0x1a00000
	v_readlane_b32 s6, v254, 3
	v_lshlrev_b32_e32 v37, 3, v0
	v_bitop3_b32 v43, v1, s3, v162 bitop3:0x48
	v_bitop3_b32 v55, v40, s3, v162 bitop3:0x48
	s_addc_u32 s21, s83, 0
	s_lshl_b32 s3, s6, 10
	v_and_b32_e32 v48, 62, v1
	v_and_b32_e32 v38, 0x78, v37
	v_mov_b32_e32 v37, 0
	s_or_b32 s30, s3, 0x80
	s_lshl_b32 s3, s6, 6
	v_lshl_add_u32 v42, v1, 8, 0
	v_lshl_add_u32 v54, v40, 8, 0
	v_lshlrev_b32_e32 v40, 2, v48
	v_mov_b32_e32 v41, v37
	s_or_b32 s31, s3, 8
	s_lshl_b32 s3, s6, 4
	s_mov_b32 s7, 0
	v_cmp_eq_u32_e64 s[4:5], 0, v164
	v_lshl_add_u64 v[40:41], s[62:63], 0, v[40:41]
	s_or_b32 s33, s3, 2
	v_add_u32_e32 v53, v42, v43
	v_add_u32_e32 v52, v44, v45
	v_add_u32_e32 v51, v46, v51
	v_add_u32_e32 v46, v54, v55
	s_mov_b32 s34, 0
	v_readlane_b32 s49, v254, 47
	v_readlane_b32 s50, v254, 48
	v_readlane_b32 s51, v254, 49
	v_readlane_b32 s52, v254, 50
	v_readlane_b32 s53, v254, 51
	v_readlane_b32 s54, v254, 52
	v_readlane_b32 s55, v254, 53
	v_readlane_b32 s56, v254, 54
	v_readlane_b32 s57, v254, 55
	v_readlane_b32 s58, v254, 56
	v_readlane_b32 s59, v254, 57
	v_readlane_b32 s60, v254, 58
	v_readlane_b32 s61, v254, 59
	global_load_dword v238, v[34:35], off
	global_load_dword v238, v[34:35], off
	global_load_dword v238, v[34:35], off
	global_load_dword v238, v[34:35], off
	s_add_i32 s6, s28, s34
	s_cmpk_gt_i32 s6, 0xfe
	s_mov_b64 s[26:27], -1
	s_cbranch_scc0 .LBB0_471_s
	s_cmpk_gt_u32 s6, 0x4fe
	s_mov_b64 s[24:25], -1
	s_cbranch_scc0 .LBB0_469_s
	s_cmpk_gt_u32 s6, 0x8fe
	s_cbranch_scc0 .LBB0_466_s
	s_and_b32 s3, s30, 0x780
	s_cmpk_gt_u32 s6, 0x91e
	v_or_b32_e32 v116, s3, v1
	s_mov_b64 s[22:23], -1
	s_cbranch_scc0 .LBB0_463_s
	s_and_b32 s6, s31, 0xffffff80
	v_lshlrev_b32_e32 v114, 12, v116
	v_mov_b32_e32 v115, v37
	s_addk_i32 s6, 0xb700
	v_lshl_add_u64 v[114:115], s[8:9], 0, v[114:115]
	v_lshl_add_u64 v[114:115], s[6:7], 1, v[114:115]
	v_lshlrev_b32_e32 v118, 1, v38
	v_mov_b32_e32 v119, v37
	v_lshl_add_u64 v[42:43], v[114:115], 0, v[118:119]
	v_or_b32_e32 v114, s6, v48
	v_mov_b32_e32 v115, v37
	v_lshlrev_b64 v[114:115], 13, v[114:115]
	v_lshl_add_u64 v[114:115], s[76:77], 0, v[114:115]
	s_lshl_b32 s6, s3, 2
	v_lshl_add_u64 v[114:115], v[114:115], 0, s[6:7]
	s_mov_b64 s[22:23], 0
.LBB0_463_s:
	s_andn2_b64 vcc, exec, s[22:23]
	s_movk_i32 s22, 0x800
	s_cbranch_vccnz .LBB0_465_s
	s_and_b32 s6, s31, 0x7f80
	v_lshlrev_b32_e32 v114, 9, v116
	v_mov_b32_e32 v115, v37
	s_addk_i32 s6, 0xb800
	v_lshl_add_u64 v[114:115], s[10:11], 0, v[114:115]
	v_lshl_add_u64 v[114:115], s[6:7], 1, v[114:115]
	v_lshlrev_b32_e32 v116, 1, v38
	v_mov_b32_e32 v117, v37
	v_lshl_add_u64 v[42:43], v[114:115], 0, v[116:117]
	v_or_b32_e32 v114, s6, v48
	v_mov_b32_e32 v115, v37
	v_lshlrev_b64 v[114:115], 13, v[114:115]
	v_lshl_add_u64 v[114:115], s[72:73], 0, v[114:115]
	s_lshl_b32 s6, s3, 2
	v_lshl_add_u64 v[114:115], v[114:115], 0, s[6:7]
	s_movk_i32 s22, 0x100

.LBB0_466_s:
	s_andn2_b64 vcc, exec, s[24:25]
	s_cbranch_vccnz .LBB0_468_s
	s_and_b32 s3, s31, 0x7f80
	s_add_i32 s6, s3, 0xffffd800
	s_and_b32 s3, s30, 0x780
	v_or_b32_e32 v114, s3, v1
	v_lshlrev_b32_e32 v114, 14, v114
	v_mov_b32_e32 v115, v37
	v_lshl_add_u64 v[114:115], s[12:13], 0, v[114:115]
	v_lshl_add_u64 v[114:115], s[6:7], 1, v[114:115]
	v_lshlrev_b32_e32 v116, 1, v38
	v_mov_b32_e32 v117, v37
	v_lshl_add_u64 v[42:43], v[114:115], 0, v[116:117]
	v_or_b32_e32 v114, s6, v48
	v_mov_b32_e32 v115, v37
	v_lshlrev_b64 v[114:115], 13, v[114:115]
	v_lshl_add_u64 v[114:115], s[70:71], 0, v[114:115]
	s_lshl_b32 s6, s3, 2
	v_lshl_add_u64 v[114:115], v[114:115], 0, s[6:7]
	s_movk_i32 s22, 0x2000

.LBB0_469_s:
	s_andn2_b64 vcc, exec, s[24:25]
	s_cbranch_vccnz .LBB0_485_s
	s_and_b32 s3, s33, 0xf80
	s_add_i32 s6, s3, 0xfffffe00
	v_lshl_add_u64 v[114:115], s[6:7], 2, v[40:41]
	s_and_b32 s3, s30, 0x1f80
	v_cndmask_b32_e64 v44, v114, 0, s[18:19]
	v_or_b32_e32 v114, s3, v1
	v_cndmask_b32_e64 v45, v115, 0, s[18:19]
	v_lshlrev_b32_e32 v114, 12, v114
	v_mov_b32_e32 v115, v37
	v_lshl_add_u64 v[114:115], s[14:15], 0, v[114:115]
	v_lshl_add_u64 v[114:115], s[6:7], 1, v[114:115]
	v_lshlrev_b32_e32 v116, 1, v38
	v_mov_b32_e32 v117, v37
	v_lshl_add_u64 v[42:43], v[114:115], 0, v[116:117]
	v_or_b32_e32 v114, s6, v48
	v_mov_b32_e32 v115, v37
	v_lshlrev_b64 v[114:115], 15, v[114:115]
	v_lshl_add_u64 v[114:115], s[68:69], 0, v[114:115]
	s_lshl_b32 s6, s3, 2
	v_lshl_add_u64 v[114:115], v[114:115], 0, s[6:7]
	s_mov_b64 s[24:25], 0x2000
	s_movk_i32 s22, 0x800
	s_mov_b64 s[26:27], 0

.LBB0_472_s:
	s_and_b32 s3, s30, 0x780
	v_or_b32_e32 v114, s3, v1
	s_and_b32 s22, s31, 0xffffff80
	v_lshlrev_b32_e32 v114, 12, v114
	v_mov_b32_e32 v115, v37
	s_ashr_i32 s23, s22, 31
	v_lshl_add_u64 v[114:115], s[20:21], 0, v[114:115]
	v_lshl_add_u64 v[114:115], s[22:23], 1, v[114:115]
	v_lshlrev_b32_e32 v116, 1, v38
	v_mov_b32_e32 v117, v37
	v_lshl_add_u64 v[42:43], v[114:115], 0, v[116:117]
	v_or_b32_e32 v114, s22, v48
	v_ashrrev_i32_e32 v115, 31, v114
	v_readlane_b32 s48, v254, 46
	v_lshlrev_b64 v[114:115], 13, v[114:115]
	v_readlane_b32 s60, v254, 58
	v_readlane_b32 s61, v254, 59
	s_lshl_b32 s6, s3, 2
	s_movk_i32 s22, 0x800
	v_lshl_add_u64 v[114:115], s[60:61], 0, v[114:115]
	v_lshl_add_u64 v[114:115], v[114:115], 0, s[6:7]
	s_mov_b64 s[24:25], 0x800
	v_mov_b64_e32 v[44:45], 0
	v_readlane_b32 s49, v254, 47
	v_readlane_b32 s50, v254, 48
	v_readlane_b32 s51, v254, 49
	v_readlane_b32 s52, v254, 50
	v_readlane_b32 s53, v254, 51
	v_readlane_b32 s54, v254, 52
	v_readlane_b32 s55, v254, 53
	v_readlane_b32 s56, v254, 54
	v_readlane_b32 s57, v254, 55
	v_readlane_b32 s58, v254, 56
	v_readlane_b32 s59, v254, 57
	v_readlane_b32 s62, v254, 60
	v_readlane_b32 s63, v254, 61
.LBB0_473_s:
	v_lshl_add_u64 v[114:115], v[114:115], 0, v[36:37]
	v_lshl_add_u64 v[122:123], s[24:25], 2, v[114:115]
	global_load_dwordx4 v[114:117], v[114:115], off
	s_nop 0
	global_load_dwordx4 v[118:121], v[122:123], off
	v_mov_b32_e32 v146, 1.0
	v_mov_b32_e32 v147, 1.0
	v_mov_b32_e32 v148, 1.0
	v_mov_b32_e32 v149, 1.0
	v_mov_b32_e32 v150, 1.0
	v_mov_b32_e32 v151, 1.0
	v_mov_b32_e32 v152, 1.0
	v_mov_b32_e32 v153, 1.0
	v_cmp_ne_u64_e32 vcc, 0, v[44:45]
	s_and_saveexec_b64 s[26:27], vcc
	s_cbranch_execz .LBB0_475_s
	global_load_dwordx2 v[146:147], v[44:45], off
.LBB0_475_s:
	s_or_b64 exec, exec, s[26:27]
	s_mul_i32 s6, s24, 0x7c
	v_lshl_add_u64 v[122:123], v[122:123], 0, s[6:7]
	s_lshl_b64 s[24:25], s[24:25], 2
	v_lshl_add_u64 v[130:131], v[122:123], 0, s[24:25]
	global_load_dwordx4 v[122:125], v[122:123], off
	s_nop 0
	global_load_dwordx4 v[126:129], v[130:131], off
	s_and_saveexec_b64 s[26:27], vcc
	s_cbranch_execz .LBB0_477_s
	global_load_dwordx2 v[148:149], v[44:45], off offset:128
.LBB0_477_s:
	s_or_b64 exec, exec, s[26:27]
	v_lshl_add_u64 v[130:131], v[130:131], 0, s[6:7]
	v_lshl_add_u64 v[138:139], v[130:131], 0, s[24:25]
	global_load_dwordx4 v[130:133], v[130:131], off
	s_nop 0
	global_load_dwordx4 v[134:137], v[138:139], off
	s_and_saveexec_b64 s[26:27], vcc
	s_cbranch_execz .LBB0_479_s
	global_load_dwordx2 v[150:151], v[44:45], off offset:256
.LBB0_479_s:
	s_or_b64 exec, exec, s[26:27]
	v_lshl_add_u64 v[138:139], v[138:139], 0, s[6:7]
	v_lshl_add_u64 v[142:143], v[138:139], 0, s[24:25]
	global_load_dwordx4 v[138:141], v[138:139], off
	s_nop 0
	global_load_dwordx4 v[142:145], v[142:143], off
	s_and_saveexec_b64 s[24:25], vcc
	s_cbranch_execz .LBB0_481_s
	global_load_dwordx2 v[152:153], v[44:45], off offset:384

.Lc5_ha_sd:
	v_mov_b64_e32 v[236:237], v[42:43]
	s_mov_b32 s96, s22
	s_addk_i32 s30, 0x80
	s_add_i32 s31, s31, 8
	s_add_i32 s33, s33, 2
	global_load_dword v238, v[34:35], off
	global_load_dword v238, v[34:35], off
	global_load_dword v238, v[34:35], off
	global_load_dword v238, v[34:35], off
.LBB0_457:
	s_waitcnt vmcnt(16)
	v_mov_b64_e32 v[72:73], v[2:3]
	v_mov_b64_e32 v[74:75], v[4:5]
	v_mov_b64_e32 v[76:77], v[6:7]
	v_mov_b64_e32 v[78:79], v[8:9]
	v_mov_b64_e32 v[80:81], v[10:11]
	v_mov_b64_e32 v[82:83], v[12:13]
	v_mov_b64_e32 v[84:85], v[14:15]
	v_mov_b64_e32 v[86:87], v[16:17]
	v_mov_b64_e32 v[88:89], v[18:19]
	v_mov_b64_e32 v[90:91], v[20:21]
	v_mov_b64_e32 v[92:93], v[22:23]
	v_mov_b64_e32 v[94:95], v[24:25]
	v_mov_b64_e32 v[96:97], v[26:27]
	v_mov_b64_e32 v[98:99], v[28:29]
	v_mov_b64_e32 v[100:101], v[30:31]
	v_mov_b64_e32 v[102:103], v[32:33]
	v_mov_b64_e32 v[104:105], v[64:65]
	v_mov_b64_e32 v[106:107], v[66:67]
	v_mov_b64_e32 v[108:109], v[68:69]
	v_mov_b64_e32 v[110:111], v[70:71]
	s_add_i32 s6, s28, s34
	s_add_i32 s6, s6, 1
	s_cmp_ge_i32 s6, s29
	s_cbranch_scc1 .LBB0_482
	s_cmpk_gt_i32 s6, 0xfe
	s_mov_b64 s[26:27], -1
	s_cbranch_scc0 .LBB0_471
	s_cmpk_gt_u32 s6, 0x4fe
	s_mov_b64 s[24:25], -1
	s_cbranch_scc0 .LBB0_469
	s_cmpk_gt_u32 s6, 0x8fe
	s_cbranch_scc0 .LBB0_466
	s_and_b32 s3, s30, 0x780
	s_cmpk_gt_u32 s6, 0x91e
	v_or_b32_e32 v4, s3, v1
	s_mov_b64 s[22:23], -1
	s_cbranch_scc0 .LBB0_463
	s_and_b32 s6, s31, 0xffffff80
	v_lshlrev_b32_e32 v2, 12, v4
	v_mov_b32_e32 v3, v37
	s_addk_i32 s6, 0xb700
	v_lshl_add_u64 v[2:3], s[8:9], 0, v[2:3]
	v_lshl_add_u64 v[2:3], s[6:7], 1, v[2:3]
	v_lshlrev_b32_e32 v6, 1, v38
	v_mov_b32_e32 v7, v37
	v_lshl_add_u64 v[42:43], v[2:3], 0, v[6:7]
	v_or_b32_e32 v2, s6, v48
	v_mov_b32_e32 v3, v37
	v_lshlrev_b64 v[2:3], 13, v[2:3]
	v_lshl_add_u64 v[2:3], s[76:77], 0, v[2:3]
	s_lshl_b32 s6, s3, 2
	v_lshl_add_u64 v[2:3], v[2:3], 0, s[6:7]
	s_mov_b64 s[22:23], 0

.LBB0_482:
	s_mov_b32 s22, s2
	v_mov_b64_e32 v[42:43], v[34:35]
	s_waitcnt vmcnt(4)

.LBB0_483:
	ds_read_b128 v[54:57], v53
	s_mov_b32 s3, s7
	s_lshl_b64 s[2:3], s[2:3], 6
	s_add_i32 s34, s34, 1
	s_addk_i32 s30, 0x80
	s_waitcnt lgkmcnt(0)
	v_cndmask_b32_e64 v44, v55, v54, s[4:5]
	v_cndmask_b32_e64 v45, v54, v55, s[4:5]
	v_cndmask_b32_e64 v58, v57, v56, s[4:5]
	v_cndmask_b32_e64 v57, v56, v57, s[4:5]
	v_cndmask_b32_e64 v54, v58, v44, s[0:1]
	v_cndmask_b32_e64 v55, v57, v45, s[0:1]
	v_cndmask_b32_e64 v56, v44, v58, s[0:1]
	v_cndmask_b32_e64 v57, v45, v57, s[0:1]
	global_store_dwordx4 v[34:35], v[54:57], off
	ds_read_b128 v[54:57], v52
	v_lshl_add_u64 v[34:35], v[34:35], 0, s[2:3]
	s_add_i32 s31, s31, 8
	s_add_i32 s33, s33, 2
	s_cmp_eq_u32 s34, 7
	s_waitcnt lgkmcnt(0)
	v_cndmask_b32_e64 v44, v55, v54, s[4:5]
	v_cndmask_b32_e64 v45, v54, v55, s[4:5]
	v_cndmask_b32_e64 v58, v57, v56, s[4:5]
	v_cndmask_b32_e64 v57, v56, v57, s[4:5]
	v_cndmask_b32_e64 v54, v58, v44, s[0:1]
	v_cndmask_b32_e64 v55, v57, v45, s[0:1]
	v_cndmask_b32_e64 v56, v44, v58, s[0:1]
	v_cndmask_b32_e64 v57, v45, v57, s[0:1]
	global_store_dwordx4 v[34:35], v[54:57], off
	ds_read_b128 v[54:57], v51
	v_lshl_add_u64 v[34:35], v[34:35], 0, s[2:3]
	s_waitcnt lgkmcnt(0)
	v_cndmask_b32_e64 v44, v55, v54, s[4:5]
	v_cndmask_b32_e64 v45, v54, v55, s[4:5]
	v_cndmask_b32_e64 v58, v57, v56, s[4:5]
	v_cndmask_b32_e64 v57, v56, v57, s[4:5]
	v_cndmask_b32_e64 v54, v58, v44, s[0:1]
	v_cndmask_b32_e64 v55, v57, v45, s[0:1]
	v_cndmask_b32_e64 v56, v44, v58, s[0:1]
	v_cndmask_b32_e64 v57, v45, v57, s[0:1]
	global_store_dwordx4 v[34:35], v[54:57], off
	ds_read_b128 v[54:57], v46
	v_lshl_add_u64 v[34:35], v[34:35], 0, s[2:3]
	s_waitcnt lgkmcnt(0)
	v_cndmask_b32_e64 v44, v55, v54, s[4:5]
	v_cndmask_b32_e64 v45, v54, v55, s[4:5]
	v_cndmask_b32_e64 v58, v57, v56, s[4:5]
	v_cndmask_b32_e64 v57, v56, v57, s[4:5]
	v_cndmask_b32_e64 v54, v58, v44, s[0:1]
	v_cndmask_b32_e64 v55, v57, v45, s[0:1]
	v_cndmask_b32_e64 v56, v44, v58, s[0:1]
	v_cndmask_b32_e64 v57, v45, v57, s[0:1]
	global_store_dwordx4 v[34:35], v[54:57], off
	s_barrier
	s_mov_b32 s2, s96
	v_mov_b64_e32 v[34:35], v[236:237]
	s_mov_b32 s96, s22
	v_mov_b64_e32 v[236:237], v[42:43]
.Lc5_ha_b:
	s_waitcnt vmcnt(16)
	v_mov_b64_e32 v[72:73], v[114:115]
	v_mov_b64_e32 v[74:75], v[116:117]
	v_mov_b64_e32 v[76:77], v[118:119]
	v_mov_b64_e32 v[78:79], v[120:121]
	v_mov_b64_e32 v[80:81], v[122:123]
	v_mov_b64_e32 v[82:83], v[124:125]
	v_mov_b64_e32 v[84:85], v[126:127]
	v_mov_b64_e32 v[86:87], v[128:129]
	v_mov_b64_e32 v[88:89], v[130:131]
	v_mov_b64_e32 v[90:91], v[132:133]
	v_mov_b64_e32 v[92:93], v[134:135]
	v_mov_b64_e32 v[94:95], v[136:137]
	v_mov_b64_e32 v[96:97], v[138:139]
	v_mov_b64_e32 v[98:99], v[140:141]
	v_mov_b64_e32 v[100:101], v[142:143]
	v_mov_b64_e32 v[102:103], v[144:145]
	v_mov_b64_e32 v[104:105], v[146:147]
	v_mov_b64_e32 v[106:107], v[148:149]
	v_mov_b64_e32 v[108:109], v[150:151]
	v_mov_b64_e32 v[110:111], v[152:153]
	s_add_i32 s6, s28, s34
	s_add_i32 s6, s6, 1
	s_cmp_ge_i32 s6, s29
	s_cbranch_scc1 .LBB0_482_b
	s_cmpk_gt_i32 s6, 0xfe
	s_mov_b64 s[26:27], -1
	s_cbranch_scc0 .LBB0_471_b
	s_cmpk_gt_u32 s6, 0x4fe
	s_mov_b64 s[24:25], -1
	s_cbranch_scc0 .LBB0_469_b
	s_cmpk_gt_u32 s6, 0x8fe
	s_cbranch_scc0 .LBB0_466_b
	s_and_b32 s3, s30, 0x780
	s_cmpk_gt_u32 s6, 0x91e
	v_or_b32_e32 v116, s3, v1
	s_mov_b64 s[22:23], -1
	s_cbranch_scc0 .LBB0_463_b
	s_and_b32 s6, s31, 0xffffff80
	v_lshlrev_b32_e32 v114, 12, v116
	v_mov_b32_e32 v115, v37
	s_addk_i32 s6, 0xb700
	v_lshl_add_u64 v[114:115], s[8:9], 0, v[114:115]
	v_lshl_add_u64 v[114:115], s[6:7], 1, v[114:115]
	v_lshlrev_b32_e32 v118, 1, v38
	v_mov_b32_e32 v119, v37
	v_lshl_add_u64 v[42:43], v[114:115], 0, v[118:119]
	v_or_b32_e32 v114, s6, v48
	v_mov_b32_e32 v115, v37
	v_lshlrev_b64 v[114:115], 13, v[114:115]
	v_lshl_add_u64 v[114:115], s[76:77], 0, v[114:115]
	s_lshl_b32 s6, s3, 2
	v_lshl_add_u64 v[114:115], v[114:115], 0, s[6:7]
	s_mov_b64 s[22:23], 0

.LBB0_483_b:
	ds_read_b128 v[54:57], v53
	s_mov_b32 s3, s7
	s_lshl_b64 s[2:3], s[2:3], 6
	s_add_i32 s34, s34, 1
	s_addk_i32 s30, 0x80
	s_waitcnt lgkmcnt(0)
	v_cndmask_b32_e64 v44, v55, v54, s[4:5]
	v_cndmask_b32_e64 v45, v54, v55, s[4:5]
	v_cndmask_b32_e64 v58, v57, v56, s[4:5]
	v_cndmask_b32_e64 v57, v56, v57, s[4:5]
	v_cndmask_b32_e64 v54, v58, v44, s[0:1]
	v_cndmask_b32_e64 v55, v57, v45, s[0:1]
	v_cndmask_b32_e64 v56, v44, v58, s[0:1]
	v_cndmask_b32_e64 v57, v45, v57, s[0:1]
	global_store_dwordx4 v[34:35], v[54:57], off
	ds_read_b128 v[54:57], v52
	v_lshl_add_u64 v[34:35], v[34:35], 0, s[2:3]
	s_add_i32 s31, s31, 8
	s_add_i32 s33, s33, 2
	s_cmp_eq_u32 s34, 8
	s_waitcnt lgkmcnt(0)
	v_cndmask_b32_e64 v44, v55, v54, s[4:5]
	v_cndmask_b32_e64 v45, v54, v55, s[4:5]
	v_cndmask_b32_e64 v58, v57, v56, s[4:5]
	v_cndmask_b32_e64 v57, v56, v57, s[4:5]
	v_cndmask_b32_e64 v54, v58, v44, s[0:1]
	v_cndmask_b32_e64 v55, v57, v45, s[0:1]
	v_cndmask_b32_e64 v56, v44, v58, s[0:1]
	v_cndmask_b32_e64 v57, v45, v57, s[0:1]
	global_store_dwordx4 v[34:35], v[54:57], off
	ds_read_b128 v[54:57], v51
	v_lshl_add_u64 v[34:35], v[34:35], 0, s[2:3]
	s_waitcnt lgkmcnt(0)
	v_cndmask_b32_e64 v44, v55, v54, s[4:5]
	v_cndmask_b32_e64 v45, v54, v55, s[4:5]
	v_cndmask_b32_e64 v58, v57, v56, s[4:5]
	v_cndmask_b32_e64 v57, v56, v57, s[4:5]
	v_cndmask_b32_e64 v54, v58, v44, s[0:1]
	v_cndmask_b32_e64 v55, v57, v45, s[0:1]
	v_cndmask_b32_e64 v56, v44, v58, s[0:1]
	v_cndmask_b32_e64 v57, v45, v57, s[0:1]
	global_store_dwordx4 v[34:35], v[54:57], off
	ds_read_b128 v[54:57], v46
	v_lshl_add_u64 v[34:35], v[34:35], 0, s[2:3]
	s_waitcnt lgkmcnt(0)
	v_cndmask_b32_e64 v44, v55, v54, s[4:5]
	v_cndmask_b32_e64 v45, v54, v55, s[4:5]
	v_cndmask_b32_e64 v58, v57, v56, s[4:5]
	v_cndmask_b32_e64 v57, v56, v57, s[4:5]
	v_cndmask_b32_e64 v54, v58, v44, s[0:1]
	v_cndmask_b32_e64 v55, v57, v45, s[0:1]
	v_cndmask_b32_e64 v56, v44, v58, s[0:1]
	v_cndmask_b32_e64 v57, v45, v57, s[0:1]
	global_store_dwordx4 v[34:35], v[54:57], off
	s_barrier
	s_cbranch_scc1 .Lc5_ha_x
	s_mov_b32 s2, s96
	v_mov_b64_e32 v[34:35], v[236:237]
	s_mov_b32 s96, s22
	v_mov_b64_e32 v[236:237], v[42:43]
	s_branch .LBB0_457
.LBB0_485:
	v_mov_b64_e32 v[44:45], 0
	s_mov_b64 s[24:25], 0x800
	s_cbranch_execz .LBB0_472
	s_branch .LBB0_473
.LBB0_485_b:
	v_mov_b64_e32 v[44:45], 0
	s_mov_b64 s[24:25], 0x800
	s_cbranch_execz .LBB0_472_b
	s_branch .LBB0_473_b
.LBB0_485_s:
	v_mov_b64_e32 v[44:45], 0
	s_mov_b64 s[24:25], 0x800
	s_cbranch_execz .LBB0_472_s
	s_branch .LBB0_473_s
.Lc5_ha_x:
	s_branch .LBB0_487
.LBB0_487:
	s_mov_b64 s[0:1], 0
